# E10: previous + first 8 exps of each tile hoisted into the inter-phase LDS-DMA region of the attention loop
# baseline (speedup 1.0000x reference)
.LBB0_731:
	s_mov_b32 s44, s29
	s_mov_b32 s28, s25
	v_add_u32_e32 v195, s45, v190
	ds_read_b64_tr_b16 v[196:197], v195 offset:24576
	ds_read_b64_tr_b16 v[198:199], v195 offset:25088
	v_add_f32_e32 v88, v68, v69
	v_add_f32_e32 v88, v70, v88
	v_add_f32_e32 v88, v71, v88
	v_add_f32_e32 v88, v72, v88
	v_add_f32_e32 v88, v73, v88
	v_cvt_pk_bf16_f32 v152, v68, v69
	v_cvt_pk_bf16_f32 v153, v70, v71
	v_mfma_f32_32x32x16_bf16 v[100:115], v[84:87], v[160:163], v[36:51]
	ds_read_b64_tr_b16 v[68:69], v195 offset:28672
	ds_read_b64_tr_b16 v[70:71], v195 offset:29184
	v_add_f32_e32 v84, v74, v88
	v_add_f32_e32 v84, v75, v84
	v_add_f32_e32 v84, v76, v84
	v_add_f32_e32 v132, v77, v84
	v_mfma_f32_32x32x16_bf16 v[84:99], v[168:171], v[160:163], v[36:51]
	v_cvt_pk_bf16_f32 v154, v72, v73
	v_cvt_pk_bf16_f32 v155, v74, v75
	ds_read_b64_tr_b16 v[72:73], v195 offset:25600
	ds_read_b64_tr_b16 v[74:75], v195 offset:26112
	v_add_f32_e32 v132, v78, v132
	v_add_f32_e32 v132, v79, v132
	v_add_f32_e32 v132, v80, v132
	v_add_f32_e32 v132, v81, v132
	v_cvt_pk_bf16_f32 v148, v76, v77
	v_cvt_pk_bf16_f32 v149, v78, v79
	v_mfma_f32_32x32x16_bf16 v[100:115], v[172:175], v[156:159], v[100:115]
	ds_read_b64_tr_b16 v[76:77], v195 offset:29696
	ds_read_b64_tr_b16 v[78:79], v195 offset:30208
	v_mfma_f32_32x32x16_bf16 v[84:99], v[164:167], v[156:159], v[84:99]
	v_add_f32_e32 v132, v82, v132
	v_add_f32_e32 v132, v83, v132
	v_add_f32_e32 v132, v52, v132
	v_add_f32_e32 v132, v53, v132
	v_cvt_pk_bf16_f32 v150, v80, v81
	v_cvt_pk_bf16_f32 v151, v82, v83
	ds_read_b64_tr_b16 v[80:81], v195 offset:26624
	ds_read_b64_tr_b16 v[82:83], v195 offset:27136
	v_mfma_f32_32x32x16_bf16 v[100:115], v[128:131], v[144:147], v[100:115]
	v_add_f32_e32 v128, v54, v132
	v_add_f32_e32 v128, v55, v128
	v_add_f32_e32 v128, v56, v128
	v_add_f32_e32 v128, v57, v128
	v_cvt_pk_bf16_f32 v140, v52, v53
	v_cvt_pk_bf16_f32 v141, v54, v55
	ds_read_b64_tr_b16 v[52:53], v195 offset:30720
	ds_read_b64_tr_b16 v[54:55], v195 offset:31232
	v_mfma_f32_32x32x16_bf16 v[84:99], v[124:127], v[144:147], v[84:99]
	v_add_f32_e32 v124, v58, v128
	v_add_f32_e32 v124, v59, v124
	v_add_f32_e32 v124, v60, v124
	v_add_f32_e32 v124, v61, v124
	v_cvt_pk_bf16_f32 v142, v56, v57
	v_cvt_pk_bf16_f32 v143, v58, v59
	ds_read_b64_tr_b16 v[56:57], v195 offset:27648
	ds_read_b64_tr_b16 v[58:59], v195 offset:28160
	v_mfma_f32_32x32x16_bf16 v[100:115], v[120:123], v[136:139], v[100:115]
	v_add_f32_e32 v120, v62, v124
	v_add_f32_e32 v120, v63, v120
	v_add_f32_e32 v120, v64, v120
	v_add_f32_e32 v120, v65, v120
	v_cvt_pk_bf16_f32 v132, v60, v61
	v_cvt_pk_bf16_f32 v133, v62, v63
	ds_read_b64_tr_b16 v[60:61], v195 offset:31744
	ds_read_b64_tr_b16 v[62:63], v195 offset:32256
	v_mfma_f32_32x32x16_bf16 v[84:99], v[116:119], v[136:139], v[84:99]
	v_add_f32_e32 v116, v66, v120
	v_add_f32_e32 v195, v67, v116
	v_cvt_pk_bf16_f32 v134, v64, v65
	v_cvt_pk_bf16_f32 v135, v66, v67
	v_exp_f32_e32 v100, v100
	v_exp_f32_e32 v101, v101
	v_exp_f32_e32 v102, v102
	v_exp_f32_e32 v103, v103
	v_exp_f32_e32 v104, v104
	v_exp_f32_e32 v105, v105
	v_exp_f32_e32 v106, v106
	v_exp_f32_e32 v107, v107
	s_add_i32 m0, s25, s59
	v_lshl_add_u64 v[64:65], v[0:1], 0, s[76:77]
	global_load_lds_dwordx4 v[64:65], off
	s_add_i32 m0, s44, s58
	v_lshl_add_u64 v[64:65], v[184:185], 0, s[34:35]
	global_load_lds_dwordx4 v[64:65], off
	s_waitcnt lgkmcnt(14)
	v_mfma_f32_32x32x16_bf16 v[4:19], v[152:155], v[196:199], v[4:19]
	s_waitcnt lgkmcnt(12)
	v_mfma_f32_32x32x16_bf16 v[20:35], v[152:155], v[68:71], v[20:35]
	v_add_u32_e32 v68, s44, v191
	ds_read_b128 v[64:67], v68
	ds_read_b128 v[120:123], v68 offset:512
	s_waitcnt lgkmcnt(12)
	v_mfma_f32_32x32x16_bf16 v[4:19], v[148:151], v[72:75], v[4:19]
	v_exp_f32_e32 v108, v108
	v_exp_f32_e32 v109, v109
	v_exp_f32_e32 v110, v110
	v_exp_f32_e32 v111, v111
	ds_read_b128 v[124:127], v68 offset:2048
	ds_read_b128 v[128:131], v68 offset:2560
	s_waitcnt lgkmcnt(12)
	v_mfma_f32_32x32x16_bf16 v[20:35], v[148:151], v[76:79], v[20:35]
	v_exp_f32_e32 v112, v112
	v_exp_f32_e32 v113, v113
	v_exp_f32_e32 v114, v114
	v_exp_f32_e32 v115, v115
	ds_read_b128 v[164:167], v68 offset:4096
	ds_read_b128 v[168:171], v68 offset:4608
	s_waitcnt lgkmcnt(12)
	v_mfma_f32_32x32x16_bf16 v[4:19], v[140:143], v[80:83], v[4:19]
	v_exp_f32_e32 v84, v84
	v_exp_f32_e32 v85, v85
	v_exp_f32_e32 v86, v86
	v_exp_f32_e32 v87, v87
	ds_read_b128 v[172:175], v68 offset:6144
	ds_read_b128 v[116:119], v68 offset:6656
	s_waitcnt lgkmcnt(12)
	v_mfma_f32_32x32x16_bf16 v[20:35], v[140:143], v[52:55], v[20:35]
	v_exp_f32_e32 v88, v88
	v_exp_f32_e32 v89, v89
	v_exp_f32_e32 v90, v90
	v_exp_f32_e32 v91, v91
	s_waitcnt lgkmcnt(10)
	v_mfma_f32_32x32x16_bf16 v[4:19], v[132:135], v[56:59], v[4:19]
	v_exp_f32_e32 v92, v92
	v_exp_f32_e32 v93, v93
	v_exp_f32_e32 v94, v94
	v_exp_f32_e32 v95, v95
	s_waitcnt lgkmcnt(8)
	v_mfma_f32_32x32x16_bf16 v[20:35], v[132:135], v[60:63], v[20:35]
	v_exp_f32_e32 v96, v96
	v_exp_f32_e32 v97, v97
	v_exp_f32_e32 v98, v98
	v_exp_f32_e32 v99, v99
	s_waitcnt vmcnt(2) lgkmcnt(0)
	s_barrier
	s_add_i32 s25, s44, 0x2000
	s_cmpk_lg_i32 s44, 0x4000
	s_cselect_b32 s25, s25, 0
	v_add_u32_e32 v200, s28, v190
	ds_read_b64_tr_b16 v[196:197], v200 offset:24576
	ds_read_b64_tr_b16 v[198:199], v200 offset:25088
	v_mfma_f32_32x32x16_bf16 v[68:83], v[64:67], v[160:163], v[36:51]
	v_add_f32_e32 v52, v100, v101
	v_add_f32_e32 v52, v102, v52
	v_add_f32_e32 v52, v103, v52
	v_add_f32_e32 v52, v104, v52
	v_add_f32_e32 v52, v105, v52
	v_cvt_pk_bf16_f32 v152, v100, v101
	v_cvt_pk_bf16_f32 v153, v102, v103
	ds_read_b64_tr_b16 v[100:101], v200 offset:28672
	ds_read_b64_tr_b16 v[102:103], v200 offset:29184
	v_add_f32_e32 v52, v106, v52
	v_add_f32_e32 v52, v107, v52
	v_add_f32_e32 v52, v108, v52
	v_add_f32_e32 v132, v109, v52
	v_mfma_f32_32x32x16_bf16 v[52:67], v[120:123], v[160:163], v[36:51]
	v_cvt_pk_bf16_f32 v154, v104, v105
	v_cvt_pk_bf16_f32 v155, v106, v107
	ds_read_b64_tr_b16 v[104:105], v200 offset:25600
	ds_read_b64_tr_b16 v[106:107], v200 offset:26112
	v_mfma_f32_32x32x16_bf16 v[68:83], v[124:127], v[156:159], v[68:83]
	v_add_f32_e32 v120, v110, v132
	v_add_f32_e32 v120, v111, v120
	v_add_f32_e32 v120, v112, v120
	v_add_f32_e32 v120, v113, v120
	v_cvt_pk_bf16_f32 v148, v108, v109
	v_cvt_pk_bf16_f32 v149, v110, v111
	ds_read_b64_tr_b16 v[108:109], v200 offset:29696
	ds_read_b64_tr_b16 v[110:111], v200 offset:30208
	v_mfma_f32_32x32x16_bf16 v[52:67], v[128:131], v[156:159], v[52:67]
	v_add_f32_e32 v120, v114, v120
	v_add_f32_e32 v120, v115, v120
	v_add_f32_e32 v120, v84, v120
	v_add_f32_e32 v120, v85, v120
	v_cvt_pk_bf16_f32 v150, v112, v113
	v_cvt_pk_bf16_f32 v151, v114, v115
	ds_read_b64_tr_b16 v[112:113], v200 offset:26624
	ds_read_b64_tr_b16 v[114:115], v200 offset:27136
	v_mfma_f32_32x32x16_bf16 v[68:83], v[164:167], v[144:147], v[68:83]
	v_add_f32_e32 v120, v86, v120
	v_add_f32_e32 v120, v87, v120
	v_add_f32_e32 v120, v88, v120
	v_add_f32_e32 v120, v89, v120
	v_cvt_pk_bf16_f32 v140, v84, v85
	v_cvt_pk_bf16_f32 v141, v86, v87
	ds_read_b64_tr_b16 v[206:207], v200 offset:30720
	ds_read_b64_tr_b16 v[208:209], v200 offset:31232
	v_mfma_f32_32x32x16_bf16 v[52:67], v[168:171], v[144:147], v[52:67]
	v_add_f32_e32 v84, v90, v120
	v_add_f32_e32 v84, v91, v84
	v_add_f32_e32 v84, v92, v84
	v_add_f32_e32 v84, v93, v84
	v_cvt_pk_bf16_f32 v142, v88, v89
	v_cvt_pk_bf16_f32 v143, v90, v91
	ds_read_b64_tr_b16 v[88:89], v200 offset:27648
	ds_read_b64_tr_b16 v[90:91], v200 offset:28160
	v_mfma_f32_32x32x16_bf16 v[68:83], v[172:175], v[136:139], v[68:83]
	v_add_f32_e32 v84, v94, v84
	v_add_f32_e32 v84, v95, v84
	v_add_f32_e32 v84, v96, v84
	v_add_f32_e32 v84, v97, v84
	v_cvt_pk_bf16_f32 v132, v92, v93
	v_cvt_pk_bf16_f32 v133, v94, v95
	ds_read_b64_tr_b16 v[92:93], v200 offset:31744
	ds_read_b64_tr_b16 v[94:95], v200 offset:32256
	v_mfma_f32_32x32x16_bf16 v[52:67], v[116:119], v[136:139], v[52:67]
	v_add_f32_e32 v84, v98, v84
	v_add_f32_e32 v200, v99, v84
	v_cvt_pk_bf16_f32 v134, v96, v97
	v_cvt_pk_bf16_f32 v135, v98, v99
	v_exp_f32_e32 v68, v68
	v_exp_f32_e32 v69, v69
	v_exp_f32_e32 v70, v70
	v_exp_f32_e32 v71, v71
	v_exp_f32_e32 v72, v72
	v_exp_f32_e32 v73, v73
	v_exp_f32_e32 v74, v74
	v_exp_f32_e32 v75, v75
	s_mov_b64 s[28:29], 0x10000
	s_add_i32 m0, s44, s59
	v_lshl_add_u64 v[84:85], v[0:1], 0, s[28:29]
	global_load_lds_dwordx4 v[84:85], off
	s_add_i32 m0, s25, s58
	v_lshl_add_u64 v[184:185], v[184:185], 0, s[36:37]
	global_load_lds_dwordx4 v[184:185], off
	s_waitcnt lgkmcnt(14)
	v_mfma_f32_32x32x16_bf16 v[4:19], v[152:155], v[196:199], v[4:19]
	s_waitcnt lgkmcnt(12)
	v_mfma_f32_32x32x16_bf16 v[20:35], v[152:155], v[100:103], v[20:35]
	v_add_u32_e32 v96, s25, v191
	ds_read_b128 v[84:87], v96
	ds_read_b128 v[168:171], v96 offset:512
	s_waitcnt lgkmcnt(12)
	v_mfma_f32_32x32x16_bf16 v[4:19], v[148:151], v[104:107], v[4:19]
	v_exp_f32_e32 v76, v76
	v_exp_f32_e32 v77, v77
	v_exp_f32_e32 v78, v78
	v_exp_f32_e32 v79, v79
	ds_read_b128 v[172:175], v96 offset:2048
	ds_read_b128 v[164:167], v96 offset:2560
	s_waitcnt lgkmcnt(12)
	v_mfma_f32_32x32x16_bf16 v[20:35], v[148:151], v[108:111], v[20:35]
	v_exp_f32_e32 v80, v80
	v_exp_f32_e32 v81, v81
	v_exp_f32_e32 v82, v82
	v_exp_f32_e32 v83, v83
	ds_read_b128 v[128:131], v96 offset:4096
	ds_read_b128 v[124:127], v96 offset:4608
	s_waitcnt lgkmcnt(12)
	v_mfma_f32_32x32x16_bf16 v[4:19], v[140:143], v[112:115], v[4:19]
	v_exp_f32_e32 v52, v52
	v_exp_f32_e32 v53, v53
	v_exp_f32_e32 v54, v54
	v_exp_f32_e32 v55, v55
	ds_read_b128 v[120:123], v96 offset:6144
	ds_read_b128 v[116:119], v96 offset:6656
	s_waitcnt lgkmcnt(12)
	v_mfma_f32_32x32x16_bf16 v[20:35], v[140:143], v[206:209], v[20:35]
	v_exp_f32_e32 v56, v56
	v_exp_f32_e32 v57, v57
	v_exp_f32_e32 v58, v58
	v_exp_f32_e32 v59, v59
	s_waitcnt lgkmcnt(10)
	v_mfma_f32_32x32x16_bf16 v[4:19], v[132:135], v[88:91], v[4:19]
	v_exp_f32_e32 v60, v60
	v_exp_f32_e32 v61, v61
	v_exp_f32_e32 v62, v62
	v_exp_f32_e32 v63, v63
	s_waitcnt lgkmcnt(8)
	v_mfma_f32_32x32x16_bf16 v[20:35], v[132:135], v[92:95], v[20:35]
	v_exp_f32_e32 v64, v64
	v_exp_f32_e32 v65, v65
	v_exp_f32_e32 v66, v66
	v_exp_f32_e32 v67, v67
	s_add_i32 s28, s25, 0x2000
	s_waitcnt vmcnt(2) lgkmcnt(0)
	s_barrier
	s_cmpk_lg_i32 s25, 0x4000
	v_add_f32_e32 v88, v192, v195
	s_cselect_b32 s29, s28, 0
	s_add_i32 s24, s24, 2
	v_add_f32_e32 v192, v88, v200
	v_lshl_add_u64 v[0:1], v[0:1], 0, s[36:37]
	s_cmpk_gt_u32 s24, 0xf8
	s_mov_b32 s45, s44
	s_cbranch_scc0 .LBB0_731
	s_and_b32 s24, s60, 0x3fffffc0
	s_cmp_lg_u32 0, -1
	s_cselect_b32 s28, 0, 0
	s_addk_i32 s28, 0x6000
	s_lshl_b32 s24, s24, 2
	v_add3_u32 v0, v194, s28, v193
	s_add_i32 s28, s24, 0
	v_add_u32_e32 v1, s44, v190
	ds_read_b64_tr_b16 v[194:195], v1 offset:24576
	ds_read_b64_tr_b16 v[196:197], v1 offset:25088
	v_add_f32_e32 v88, v68, v69
	v_add_f32_e32 v88, v70, v88
	v_add_f32_e32 v88, v71, v88
	v_add_f32_e32 v88, v72, v88
	v_add_f32_e32 v88, v73, v88
	v_cvt_pk_bf16_f32 v152, v68, v69
	v_cvt_pk_bf16_f32 v153, v70, v71
	s_waitcnt lgkmcnt(9)
	v_mfma_f32_32x32x16_bf16 v[100:115], v[84:87], v[160:163], v[36:51]
	ds_read_b64_tr_b16 v[68:69], v1 offset:28672
	ds_read_b64_tr_b16 v[70:71], v1 offset:29184
	v_add_f32_e32 v84, v74, v88
	v_add_f32_e32 v84, v75, v84
	v_add_f32_e32 v84, v76, v84
	v_add_f32_e32 v132, v77, v84
	v_cvt_pk_bf16_f32 v154, v72, v73
	v_cvt_pk_bf16_f32 v155, v74, v75
	s_waitcnt lgkmcnt(10)
	v_mfma_f32_32x32x16_bf16 v[84:99], v[168:171], v[160:163], v[36:51]
	ds_read_b64_tr_b16 v[72:73], v1 offset:25600
	ds_read_b64_tr_b16 v[74:75], v1 offset:26112
	v_add_f32_e32 v132, v78, v132
	v_add_f32_e32 v132, v79, v132
	v_add_f32_e32 v132, v80, v132
	v_add_f32_e32 v132, v81, v132
	v_cvt_pk_bf16_f32 v148, v76, v77
	v_cvt_pk_bf16_f32 v149, v78, v79
	s_waitcnt lgkmcnt(11)
	v_mfma_f32_32x32x16_bf16 v[100:115], v[172:175], v[156:159], v[100:115]
	ds_read_b64_tr_b16 v[76:77], v1 offset:29696
	ds_read_b64_tr_b16 v[78:79], v1 offset:30208
	v_add_f32_e32 v132, v82, v132
	v_add_f32_e32 v132, v83, v132
	v_add_f32_e32 v132, v52, v132
	v_add_f32_e32 v132, v53, v132
	v_cvt_pk_bf16_f32 v150, v80, v81
	v_cvt_pk_bf16_f32 v151, v82, v83
	s_waitcnt lgkmcnt(12)
	v_mfma_f32_32x32x16_bf16 v[84:99], v[164:167], v[156:159], v[84:99]
	ds_read_b64_tr_b16 v[80:81], v1 offset:26624
	ds_read_b64_tr_b16 v[82:83], v1 offset:27136
	s_waitcnt lgkmcnt(13)
	v_mfma_f32_32x32x16_bf16 v[100:115], v[128:131], v[144:147], v[100:115]
	v_add_f32_e32 v128, v54, v132
	v_add_f32_e32 v128, v55, v128
	v_add_f32_e32 v128, v56, v128
	v_add_f32_e32 v128, v57, v128
	v_cvt_pk_bf16_f32 v140, v52, v53
	v_cvt_pk_bf16_f32 v141, v54, v55
	ds_read_b64_tr_b16 v[52:53], v1 offset:30720
	ds_read_b64_tr_b16 v[54:55], v1 offset:31232
	s_waitcnt lgkmcnt(14)
	v_mfma_f32_32x32x16_bf16 v[84:99], v[124:127], v[144:147], v[84:99]
	v_add_f32_e32 v124, v58, v128
	v_add_f32_e32 v124, v59, v124
	v_add_f32_e32 v124, v60, v124
	v_add_f32_e32 v124, v61, v124
	v_cvt_pk_bf16_f32 v142, v56, v57
	v_cvt_pk_bf16_f32 v143, v58, v59
	ds_read_b64_tr_b16 v[56:57], v1 offset:27648
	ds_read_b64_tr_b16 v[58:59], v1 offset:28160
	s_waitcnt lgkmcnt(14)
	v_mfma_f32_32x32x16_bf16 v[100:115], v[120:123], v[136:139], v[100:115]
	v_add_f32_e32 v120, v62, v124
	v_add_f32_e32 v120, v63, v120
	v_add_f32_e32 v120, v64, v120
	v_add_f32_e32 v120, v65, v120
	v_cvt_pk_bf16_f32 v132, v60, v61
	v_cvt_pk_bf16_f32 v133, v62, v63
	ds_read_b64_tr_b16 v[60:61], v1 offset:31744
	ds_read_b64_tr_b16 v[62:63], v1 offset:32256
	v_add_f32_e32 v1, v66, v120
	v_add_f32_e32 v1, v67, v1
	v_add_f32_e32 v1, 0, v1
	v_cvt_pk_bf16_f32 v134, v64, v65
	v_cvt_pk_bf16_f32 v135, v66, v67
	v_mfma_f32_32x32x16_bf16 v[84:99], v[116:119], v[136:139], v[84:99]
	s_mov_b64 s[46:47], 0x3f8000
	s_add_i32 s24, s25, s59
	v_lshl_add_u64 v[64:65], v[182:183], 0, s[46:47]
	s_mov_b32 s44, m0
	s_mov_b32 m0, s24
	s_nop 0
	global_load_lds_dwordx4 v[64:65], off
	s_mov_b32 m0, s44
	s_mov_b64 s[44:45], 0x3f0000
	v_lshl_add_u64 v[64:65], v[180:181], 0, s[44:45]
	s_add_i32 s24, s29, s58
	s_mov_b32 s44, m0
	s_mov_b32 m0, s24
	s_nop 0
	global_load_lds_dwordx4 v[64:65], off
	s_mov_b32 m0, s44
	v_add_f32_e32 v1, v192, v1
	s_waitcnt lgkmcnt(14)
	v_mfma_f32_32x32x16_bf16 v[4:19], v[152:155], v[194:197], v[4:19]
	v_exp_f32_e32 v100, v100
	v_exp_f32_e32 v101, v101
	v_exp_f32_e32 v102, v102
	v_exp_f32_e32 v103, v103
	s_waitcnt lgkmcnt(12)
	v_mfma_f32_32x32x16_bf16 v[20:35], v[152:155], v[68:71], v[20:35]
	v_exp_f32_e32 v104, v104
	v_exp_f32_e32 v105, v105
	v_exp_f32_e32 v106, v106
	v_exp_f32_e32 v107, v107
	v_add_u32_e32 v68, s29, v191
	ds_read_b128 v[64:67], v68
	ds_read_b128 v[164:167], v68 offset:512
	s_waitcnt lgkmcnt(12)
	v_mfma_f32_32x32x16_bf16 v[4:19], v[148:151], v[72:75], v[4:19]
	v_exp_f32_e32 v108, v108
	v_exp_f32_e32 v109, v109
	v_exp_f32_e32 v110, v110
	v_exp_f32_e32 v111, v111
	ds_read_b128 v[72:75], v68 offset:2048
	ds_read_b128 v[168:171], v68 offset:2560
	s_waitcnt lgkmcnt(12)
	v_mfma_f32_32x32x16_bf16 v[20:35], v[148:151], v[76:79], v[20:35]
	v_exp_f32_e32 v112, v112
	v_exp_f32_e32 v113, v113
	v_exp_f32_e32 v114, v114
	v_exp_f32_e32 v115, v115
	ds_read_b128 v[76:79], v68 offset:4096
	ds_read_b128 v[172:175], v68 offset:4608
	s_waitcnt lgkmcnt(12)
	v_mfma_f32_32x32x16_bf16 v[4:19], v[140:143], v[80:83], v[4:19]
	v_exp_f32_e32 v84, v84
	v_exp_f32_e32 v85, v85
	v_exp_f32_e32 v86, v86
	v_exp_f32_e32 v87, v87
	ds_read_b128 v[80:83], v68 offset:6144
	ds_read_b128 v[68:71], v68 offset:6656
	s_waitcnt lgkmcnt(12)
	v_mfma_f32_32x32x16_bf16 v[20:35], v[140:143], v[52:55], v[20:35]
	v_exp_f32_e32 v88, v88
	v_exp_f32_e32 v89, v89
	v_exp_f32_e32 v90, v90
	v_exp_f32_e32 v91, v91
	s_waitcnt lgkmcnt(10)
	v_mfma_f32_32x32x16_bf16 v[4:19], v[132:135], v[56:59], v[4:19]
	v_exp_f32_e32 v92, v92
	v_exp_f32_e32 v93, v93
	v_exp_f32_e32 v94, v94
	v_exp_f32_e32 v95, v95
	s_waitcnt lgkmcnt(8)
	v_mfma_f32_32x32x16_bf16 v[20:35], v[132:135], v[60:63], v[20:35]
	v_exp_f32_e32 v96, v96
	v_exp_f32_e32 v97, v97
	v_exp_f32_e32 v98, v98
	v_exp_f32_e32 v99, v99
	s_waitcnt vmcnt(2) lgkmcnt(0)
	s_barrier
	s_add_i32 s24, s29, 0x2000
	s_cmpk_lg_i32 s29, 0x4000
	s_cselect_b32 s44, s24, 0
	v_add_u32_e32 v184, s25, v190
	ds_read_b64_tr_b16 v[192:193], v184 offset:24576
	ds_read_b64_tr_b16 v[194:195], v184 offset:25088
	v_add_f32_e32 v52, v100, v101
	v_add_f32_e32 v52, v102, v52
	v_add_f32_e32 v52, v103, v52
	v_add_f32_e32 v52, v104, v52
	v_add_f32_e32 v52, v105, v52
	v_cvt_pk_bf16_f32 v152, v100, v101
	v_cvt_pk_bf16_f32 v153, v102, v103
	s_waitcnt lgkmcnt(9)
	v_mfma_f32_32x32x16_bf16 v[116:131], v[64:67], v[160:163], v[36:51]
	ds_read_b64_tr_b16 v[100:101], v184 offset:28672
	ds_read_b64_tr_b16 v[102:103], v184 offset:29184
	v_add_f32_e32 v52, v106, v52
	v_add_f32_e32 v52, v107, v52
	v_add_f32_e32 v52, v108, v52
	v_add_f32_e32 v132, v109, v52
	v_cvt_pk_bf16_f32 v154, v104, v105
	v_cvt_pk_bf16_f32 v155, v106, v107
	s_waitcnt lgkmcnt(10)
	v_mfma_f32_32x32x16_bf16 v[52:67], v[164:167], v[160:163], v[36:51]
	ds_read_b64_tr_b16 v[104:105], v184 offset:25600
	ds_read_b64_tr_b16 v[106:107], v184 offset:26112
	s_waitcnt lgkmcnt(11)
	v_mfma_f32_32x32x16_bf16 v[116:131], v[72:75], v[156:159], v[116:131]
	v_add_f32_e32 v72, v110, v132
	v_add_f32_e32 v72, v111, v72
	v_add_f32_e32 v72, v112, v72
	v_add_f32_e32 v132, v113, v72
	v_cvt_pk_bf16_f32 v148, v108, v109
	v_cvt_pk_bf16_f32 v149, v110, v111
	ds_read_b64_tr_b16 v[72:73], v184 offset:29696
	ds_read_b64_tr_b16 v[74:75], v184 offset:30208
	v_add_f32_e32 v108, v114, v132
	v_add_f32_e32 v108, v115, v108
	v_add_f32_e32 v108, v84, v108
	v_add_f32_e32 v132, v85, v108
	v_cvt_pk_bf16_f32 v150, v112, v113
	v_cvt_pk_bf16_f32 v151, v114, v115
	s_waitcnt lgkmcnt(12)
	v_mfma_f32_32x32x16_bf16 v[52:67], v[168:171], v[156:159], v[52:67]
	ds_read_b64_tr_b16 v[108:109], v184 offset:26624
	ds_read_b64_tr_b16 v[110:111], v184 offset:27136
	s_waitcnt lgkmcnt(13)
	v_mfma_f32_32x32x16_bf16 v[116:131], v[76:79], v[144:147], v[116:131]
	v_add_f32_e32 v76, v86, v132
	v_add_f32_e32 v76, v87, v76
	v_add_f32_e32 v76, v88, v76
	v_add_f32_e32 v112, v89, v76
	v_cvt_pk_bf16_f32 v140, v84, v85
	v_cvt_pk_bf16_f32 v141, v86, v87
	ds_read_b64_tr_b16 v[76:77], v184 offset:30720
	ds_read_b64_tr_b16 v[78:79], v184 offset:31232
	v_add_f32_e32 v84, v90, v112
	v_add_f32_e32 v84, v91, v84
	v_add_f32_e32 v84, v92, v84
	v_add_f32_e32 v84, v93, v84
	v_cvt_pk_bf16_f32 v142, v88, v89
	v_cvt_pk_bf16_f32 v143, v90, v91
	s_waitcnt lgkmcnt(14)
	v_mfma_f32_32x32x16_bf16 v[52:67], v[172:175], v[144:147], v[52:67]
	ds_read_b64_tr_b16 v[88:89], v184 offset:27648
	ds_read_b64_tr_b16 v[90:91], v184 offset:28160
	s_waitcnt lgkmcnt(14)
	v_mfma_f32_32x32x16_bf16 v[116:131], v[80:83], v[136:139], v[116:131]
	v_add_f32_e32 v80, v94, v84
	v_add_f32_e32 v80, v95, v80
	v_add_f32_e32 v80, v96, v80
	v_add_f32_e32 v84, v97, v80
	v_cvt_pk_bf16_f32 v132, v92, v93
	v_cvt_pk_bf16_f32 v133, v94, v95
	ds_read_b64_tr_b16 v[80:81], v184 offset:31744
	ds_read_b64_tr_b16 v[82:83], v184 offset:32256
	v_mfma_f32_32x32x16_bf16 v[52:67], v[68:71], v[136:139], v[52:67]
	v_add_f32_e32 v68, v98, v84
	v_add_f32_e32 v68, v99, v68
	v_add_f32_e32 v68, 0, v68
	v_cvt_pk_bf16_f32 v134, v96, v97
	v_cvt_pk_bf16_f32 v135, v98, v99
	s_mov_b64 s[60:61], 0x3fc000
	v_add_f32_e32 v1, v1, v68
	s_add_i32 s24, s29, s59
	v_lshl_add_u64 v[68:69], v[182:183], 0, s[60:61]
	s_mov_b32 s25, m0
	s_mov_b32 m0, s24
	s_nop 0
	global_load_lds_dwordx4 v[68:69], off
	s_mov_b32 m0, s25
	s_mov_b64 s[24:25], 0x3f4000
	s_add_i32 s45, s44, s58
	v_lshl_add_u64 v[68:69], v[180:181], 0, s[24:25]
	s_mov_b32 s24, m0
	s_mov_b32 m0, s45
	s_nop 0
	global_load_lds_dwordx4 v[68:69], off
	s_mov_b32 m0, s24
	s_waitcnt lgkmcnt(14)
	v_mfma_f32_32x32x16_bf16 v[4:19], v[152:155], v[192:195], v[4:19]
	v_exp_f32_e32 v116, v116
	v_exp_f32_e32 v117, v117
	v_exp_f32_e32 v118, v118
	v_exp_f32_e32 v119, v119
	s_waitcnt lgkmcnt(12)
	v_mfma_f32_32x32x16_bf16 v[20:35], v[152:155], v[100:103], v[20:35]
	v_exp_f32_e32 v120, v120
	v_exp_f32_e32 v121, v121
	v_exp_f32_e32 v122, v122
	v_exp_f32_e32 v123, v123
	v_add_u32_e32 v84, s44, v191
	ds_read_b128 v[68:71], v84
	ds_read_b128 v[92:95], v84 offset:512
	s_waitcnt lgkmcnt(12)
	v_mfma_f32_32x32x16_bf16 v[4:19], v[148:151], v[104:107], v[4:19]
	v_exp_f32_e32 v124, v124
	v_exp_f32_e32 v125, v125
	v_exp_f32_e32 v126, v126
	v_exp_f32_e32 v127, v127
	ds_read_b128 v[96:99], v84 offset:2048
	ds_read_b128 v[164:167], v84 offset:2560
	s_waitcnt lgkmcnt(12)
	v_mfma_f32_32x32x16_bf16 v[20:35], v[148:151], v[72:75], v[20:35]
	v_exp_f32_e32 v128, v128
	v_exp_f32_e32 v129, v129
	v_exp_f32_e32 v130, v130
	v_exp_f32_e32 v131, v131
	ds_read_b128 v[168:171], v84 offset:4096
	ds_read_b128 v[172:175], v84 offset:4608
	s_waitcnt lgkmcnt(12)
	v_mfma_f32_32x32x16_bf16 v[4:19], v[140:143], v[108:111], v[4:19]
	v_exp_f32_e32 v52, v52
	v_exp_f32_e32 v53, v53
	v_exp_f32_e32 v54, v54
	v_exp_f32_e32 v55, v55
	ds_read_b128 v[182:185], v84 offset:6144
	ds_read_b128 v[84:87], v84 offset:6656
	s_waitcnt lgkmcnt(12)
	v_mfma_f32_32x32x16_bf16 v[20:35], v[140:143], v[76:79], v[20:35]
	v_exp_f32_e32 v56, v56
	v_exp_f32_e32 v57, v57
	v_exp_f32_e32 v58, v58
	v_exp_f32_e32 v59, v59
	s_waitcnt lgkmcnt(10)
	v_mfma_f32_32x32x16_bf16 v[4:19], v[132:135], v[88:91], v[4:19]
	v_exp_f32_e32 v60, v60
	v_exp_f32_e32 v61, v61
	v_exp_f32_e32 v62, v62
	v_exp_f32_e32 v63, v63
	s_waitcnt lgkmcnt(8)
	v_mfma_f32_32x32x16_bf16 v[20:35], v[132:135], v[80:83], v[20:35]
	v_exp_f32_e32 v64, v64
	v_exp_f32_e32 v65, v65
	v_exp_f32_e32 v66, v66
	v_exp_f32_e32 v67, v67
	s_waitcnt vmcnt(2) lgkmcnt(0)
	s_barrier
	s_add_i32 s24, s44, 0x2000
	s_cmpk_lg_i32 s44, 0x4000
	s_cselect_b32 s25, s24, 0
	v_add_u32_e32 v192, s29, v190
	ds_read_b64_tr_b16 v[88:89], v192 offset:24576
	ds_read_b64_tr_b16 v[90:91], v192 offset:25088
	v_add_f32_e32 v72, v116, v117
	v_add_f32_e32 v72, v118, v72
	v_add_f32_e32 v72, v119, v72
	v_add_f32_e32 v72, v120, v72
	v_add_f32_e32 v72, v121, v72
	v_cvt_pk_bf16_f32 v152, v116, v117
	v_cvt_pk_bf16_f32 v153, v118, v119
	s_waitcnt lgkmcnt(9)
	v_mfma_f32_32x32x16_bf16 v[100:115], v[68:71], v[160:163], v[36:51]
	ds_read_b64_tr_b16 v[116:117], v192 offset:28672
	ds_read_b64_tr_b16 v[118:119], v192 offset:29184
	v_add_f32_e32 v68, v122, v72
	v_add_f32_e32 v68, v123, v68
	v_add_f32_e32 v68, v124, v68
	v_add_f32_e32 v132, v125, v68
	v_cvt_pk_bf16_f32 v154, v120, v121
	v_cvt_pk_bf16_f32 v155, v122, v123
	s_waitcnt lgkmcnt(10)
	v_mfma_f32_32x32x16_bf16 v[68:83], v[92:95], v[160:163], v[36:51]
	ds_read_b64_tr_b16 v[92:93], v192 offset:25600
	ds_read_b64_tr_b16 v[94:95], v192 offset:26112
	s_waitcnt lgkmcnt(11)
	v_mfma_f32_32x32x16_bf16 v[100:115], v[96:99], v[156:159], v[100:115]
	v_add_f32_e32 v96, v126, v132
	v_add_f32_e32 v96, v127, v96
	v_add_f32_e32 v96, v128, v96
	v_add_f32_e32 v120, v129, v96
	v_cvt_pk_bf16_f32 v148, v124, v125
	v_cvt_pk_bf16_f32 v149, v126, v127
	ds_read_b64_tr_b16 v[96:97], v192 offset:29696
	ds_read_b64_tr_b16 v[98:99], v192 offset:30208
	v_add_f32_e32 v120, v130, v120
	v_add_f32_e32 v120, v131, v120
	v_add_f32_e32 v120, v52, v120
	v_add_f32_e32 v124, v53, v120
	v_cvt_pk_bf16_f32 v150, v128, v129
	v_cvt_pk_bf16_f32 v151, v130, v131
	s_waitcnt lgkmcnt(12)
	v_mfma_f32_32x32x16_bf16 v[68:83], v[164:167], v[156:159], v[68:83]
	ds_read_b64_tr_b16 v[120:121], v192 offset:26624
	ds_read_b64_tr_b16 v[122:123], v192 offset:27136
	v_add_f32_e32 v124, v54, v124
	v_add_f32_e32 v124, v55, v124
	v_add_f32_e32 v124, v56, v124
	v_add_f32_e32 v124, v57, v124
	v_cvt_pk_bf16_f32 v140, v52, v53
	v_cvt_pk_bf16_f32 v141, v54, v55
	s_waitcnt lgkmcnt(13)
	v_mfma_f32_32x32x16_bf16 v[100:115], v[168:171], v[144:147], v[100:115]
	ds_read_b64_tr_b16 v[52:53], v192 offset:30720
	ds_read_b64_tr_b16 v[54:55], v192 offset:31232
	v_add_f32_e32 v124, v58, v124
	v_add_f32_e32 v124, v59, v124
	v_add_f32_e32 v124, v60, v124
	v_add_f32_e32 v124, v61, v124
	v_cvt_pk_bf16_f32 v142, v56, v57
	v_cvt_pk_bf16_f32 v143, v58, v59
	s_waitcnt lgkmcnt(14)
	v_mfma_f32_32x32x16_bf16 v[68:83], v[172:175], v[144:147], v[68:83]
	ds_read_b64_tr_b16 v[56:57], v192 offset:27648
	ds_read_b64_tr_b16 v[58:59], v192 offset:28160
	v_add_f32_e32 v124, v62, v124
	v_add_f32_e32 v124, v63, v124
	v_add_f32_e32 v124, v64, v124
	v_add_f32_e32 v124, v65, v124
	v_cvt_pk_bf16_f32 v132, v60, v61
	v_cvt_pk_bf16_f32 v133, v62, v63
	s_waitcnt lgkmcnt(14)
	v_mfma_f32_32x32x16_bf16 v[100:115], v[182:185], v[136:139], v[100:115]
	ds_read_b64_tr_b16 v[60:61], v192 offset:31744
	ds_read_b64_tr_b16 v[62:63], v192 offset:32256
	v_mfma_f32_32x32x16_bf16 v[68:83], v[84:87], v[136:139], v[68:83]
	v_add_f32_e32 v84, v66, v124
	v_add_f32_e32 v84, v67, v84
	v_add_f32_e32 v84, 0, v84
	v_cvt_pk_bf16_f32 v134, v64, v65
	v_cvt_pk_bf16_f32 v135, v66, v67
	v_lshl_add_u64 v[64:65], v[180:181], 0, s[46:47]
	s_add_i32 s24, s25, s58
	s_mov_b32 s29, m0
	s_mov_b32 m0, s24
	s_nop 0
	global_load_lds_dwordx4 v[64:65], off
	s_mov_b32 m0, s29
	v_add_f32_e32 v1, v1, v84
	s_waitcnt lgkmcnt(14)
	v_mfma_f32_32x32x16_bf16 v[4:19], v[152:155], v[88:91], v[4:19]
	v_exp_f32_e32 v100, v100
	v_exp_f32_e32 v101, v101
	v_exp_f32_e32 v102, v102
	v_exp_f32_e32 v103, v103
	s_waitcnt lgkmcnt(12)
	v_mfma_f32_32x32x16_bf16 v[20:35], v[152:155], v[116:119], v[20:35]
	v_exp_f32_e32 v104, v104
	v_exp_f32_e32 v105, v105
	v_exp_f32_e32 v106, v106
	v_exp_f32_e32 v107, v107
	v_add_u32_e32 v84, s25, v191
	ds_read_b128 v[64:67], v84
	ds_read_b128 v[124:127], v84 offset:512
	s_waitcnt lgkmcnt(12)
	v_mfma_f32_32x32x16_bf16 v[4:19], v[148:151], v[92:95], v[4:19]
	v_exp_f32_e32 v108, v108
	v_exp_f32_e32 v109, v109
	v_exp_f32_e32 v110, v110
	v_exp_f32_e32 v111, v111
	ds_read_b128 v[128:131], v84 offset:2048
	ds_read_b128 v[164:167], v84 offset:2560
	s_waitcnt lgkmcnt(12)
	v_mfma_f32_32x32x16_bf16 v[20:35], v[148:151], v[96:99], v[20:35]
	v_exp_f32_e32 v112, v112
	v_exp_f32_e32 v113, v113
	v_exp_f32_e32 v114, v114
	v_exp_f32_e32 v115, v115
	ds_read_b128 v[168:171], v84 offset:4096
	ds_read_b128 v[172:175], v84 offset:4608
	s_waitcnt lgkmcnt(12)
	v_mfma_f32_32x32x16_bf16 v[4:19], v[140:143], v[120:123], v[4:19]
	v_exp_f32_e32 v68, v68
	v_exp_f32_e32 v69, v69
	v_exp_f32_e32 v70, v70
	v_exp_f32_e32 v71, v71
	ds_read_b128 v[120:123], v84 offset:6144
	ds_read_b128 v[116:119], v84 offset:6656
	s_waitcnt lgkmcnt(12)
	v_mfma_f32_32x32x16_bf16 v[20:35], v[140:143], v[52:55], v[20:35]
	v_exp_f32_e32 v72, v72
	v_exp_f32_e32 v73, v73
	v_exp_f32_e32 v74, v74
	v_exp_f32_e32 v75, v75
	s_waitcnt lgkmcnt(10)
	v_mfma_f32_32x32x16_bf16 v[4:19], v[132:135], v[56:59], v[4:19]
	v_exp_f32_e32 v76, v76
	v_exp_f32_e32 v77, v77
	v_exp_f32_e32 v78, v78
	v_exp_f32_e32 v79, v79
	s_waitcnt lgkmcnt(8)
	v_mfma_f32_32x32x16_bf16 v[20:35], v[132:135], v[60:63], v[20:35]
	v_exp_f32_e32 v80, v80
	v_exp_f32_e32 v81, v81
	v_exp_f32_e32 v82, v82
	v_exp_f32_e32 v83, v83
	s_waitcnt vmcnt(1) lgkmcnt(0)
	s_barrier
	s_add_i32 s24, s25, 0x2000
	s_cmpk_lg_i32 s25, 0x4000
	s_cselect_b32 s24, s24, 0
	v_add_u32_e32 v192, s44, v190
	ds_read_b64_tr_b16 v[182:183], v192 offset:24576
	ds_read_b64_tr_b16 v[184:185], v192 offset:25088
	v_add_f32_e32 v52, v100, v101
	v_add_f32_e32 v52, v102, v52
	v_add_f32_e32 v52, v103, v52
	v_add_f32_e32 v52, v104, v52
	v_add_f32_e32 v52, v105, v52
	v_cvt_pk_bf16_f32 v152, v100, v101
	v_cvt_pk_bf16_f32 v153, v102, v103
	s_waitcnt lgkmcnt(9)
	v_mfma_f32_32x32x16_bf16 v[84:99], v[64:67], v[160:163], v[36:51]
	ds_read_b64_tr_b16 v[100:101], v192 offset:28672
	ds_read_b64_tr_b16 v[102:103], v192 offset:29184
	v_add_f32_e32 v52, v106, v52
	v_add_f32_e32 v52, v107, v52
	v_add_f32_e32 v52, v108, v52
	v_add_f32_e32 v132, v109, v52
	v_cvt_pk_bf16_f32 v154, v104, v105
	v_cvt_pk_bf16_f32 v155, v106, v107
	s_waitcnt lgkmcnt(10)
	v_mfma_f32_32x32x16_bf16 v[52:67], v[124:127], v[160:163], v[36:51]
	ds_read_b64_tr_b16 v[104:105], v192 offset:25600
	ds_read_b64_tr_b16 v[106:107], v192 offset:26112
	v_add_f32_e32 v124, v110, v132
	v_add_f32_e32 v124, v111, v124
	v_add_f32_e32 v124, v112, v124
	v_add_f32_e32 v124, v113, v124
	v_cvt_pk_bf16_f32 v148, v108, v109
	v_cvt_pk_bf16_f32 v149, v110, v111
	s_waitcnt lgkmcnt(11)
	v_mfma_f32_32x32x16_bf16 v[84:99], v[128:131], v[156:159], v[84:99]
	ds_read_b64_tr_b16 v[108:109], v192 offset:29696
	ds_read_b64_tr_b16 v[110:111], v192 offset:30208
	v_add_f32_e32 v124, v114, v124
	v_add_f32_e32 v124, v115, v124
	v_add_f32_e32 v124, v68, v124
	v_add_f32_e32 v124, v69, v124
	v_cvt_pk_bf16_f32 v150, v112, v113
	v_cvt_pk_bf16_f32 v151, v114, v115
	s_waitcnt lgkmcnt(12)
	v_mfma_f32_32x32x16_bf16 v[52:67], v[164:167], v[156:159], v[52:67]
	ds_read_b64_tr_b16 v[112:113], v192 offset:26624
	ds_read_b64_tr_b16 v[114:115], v192 offset:27136
	v_add_f32_e32 v124, v70, v124
	v_add_f32_e32 v124, v71, v124
	v_add_f32_e32 v124, v72, v124
	v_add_f32_e32 v124, v73, v124
	v_cvt_pk_bf16_f32 v140, v68, v69
	v_cvt_pk_bf16_f32 v141, v70, v71
	s_waitcnt lgkmcnt(13)
	v_mfma_f32_32x32x16_bf16 v[84:99], v[168:171], v[144:147], v[84:99]
	ds_read_b64_tr_b16 v[68:69], v192 offset:30720
	ds_read_b64_tr_b16 v[70:71], v192 offset:31232
	v_add_f32_e32 v124, v74, v124
	v_add_f32_e32 v124, v75, v124
	v_add_f32_e32 v124, v76, v124
	v_add_f32_e32 v124, v77, v124
	v_cvt_pk_bf16_f32 v142, v72, v73
	v_cvt_pk_bf16_f32 v143, v74, v75
	s_waitcnt lgkmcnt(14)
	v_mfma_f32_32x32x16_bf16 v[52:67], v[172:175], v[144:147], v[52:67]
	ds_read_b64_tr_b16 v[72:73], v192 offset:27648
	ds_read_b64_tr_b16 v[74:75], v192 offset:28160
	s_waitcnt lgkmcnt(14)
	v_mfma_f32_32x32x16_bf16 v[84:99], v[120:123], v[136:139], v[84:99]
	v_add_f32_e32 v120, v78, v124
	v_add_f32_e32 v120, v79, v120
	v_add_f32_e32 v120, v80, v120
	v_add_f32_e32 v120, v81, v120
	v_cvt_pk_bf16_f32 v132, v76, v77
	v_cvt_pk_bf16_f32 v133, v78, v79
	ds_read_b64_tr_b16 v[76:77], v192 offset:31744
	ds_read_b64_tr_b16 v[78:79], v192 offset:32256
	v_mfma_f32_32x32x16_bf16 v[52:67], v[116:119], v[136:139], v[52:67]
	v_add_f32_e32 v116, v82, v120
	v_add_f32_e32 v116, v83, v116
	v_add_f32_e32 v116, 0, v116
	v_cvt_pk_bf16_f32 v134, v80, v81
	v_cvt_pk_bf16_f32 v135, v82, v83
	s_add_i32 s29, s24, s58
	v_lshl_add_u64 v[80:81], v[180:181], 0, s[60:61]
	s_mov_b32 s44, m0
	s_mov_b32 m0, s29
	s_nop 0
	global_load_lds_dwordx4 v[80:81], off
	s_mov_b32 m0, s44
	v_add_f32_e32 v1, v1, v116
	s_waitcnt lgkmcnt(14)
	v_mfma_f32_32x32x16_bf16 v[4:19], v[152:155], v[182:185], v[4:19]
	v_exp_f32_e32 v84, v84
	v_exp_f32_e32 v85, v85
	v_exp_f32_e32 v86, v86
	v_exp_f32_e32 v87, v87
	s_waitcnt lgkmcnt(12)
	v_mfma_f32_32x32x16_bf16 v[20:35], v[152:155], v[100:103], v[20:35]
	v_exp_f32_e32 v88, v88
	v_exp_f32_e32 v89, v89
	v_exp_f32_e32 v90, v90
	v_exp_f32_e32 v91, v91
	v_add_u32_e32 v80, s24, v191
	ds_read_b128 v[116:119], v80
	ds_read_b128 v[120:123], v80 offset:512
	s_waitcnt lgkmcnt(12)
	v_mfma_f32_32x32x16_bf16 v[4:19], v[148:151], v[104:107], v[4:19]
	v_exp_f32_e32 v92, v92
	v_exp_f32_e32 v93, v93
	v_exp_f32_e32 v94, v94
	v_exp_f32_e32 v95, v95
	ds_read_b128 v[104:107], v80 offset:2048
	ds_read_b128 v[124:127], v80 offset:2560
	s_waitcnt lgkmcnt(12)
	v_mfma_f32_32x32x16_bf16 v[20:35], v[148:151], v[108:111], v[20:35]
	v_exp_f32_e32 v96, v96
	v_exp_f32_e32 v97, v97
	v_exp_f32_e32 v98, v98
	v_exp_f32_e32 v99, v99
	ds_read_b128 v[108:111], v80 offset:4096
	ds_read_b128 v[128:131], v80 offset:4608
	s_waitcnt lgkmcnt(12)
	v_mfma_f32_32x32x16_bf16 v[4:19], v[140:143], v[112:115], v[4:19]
	v_exp_f32_e32 v52, v52
	v_exp_f32_e32 v53, v53
	v_exp_f32_e32 v54, v54
	v_exp_f32_e32 v55, v55
	ds_read_b128 v[112:115], v80 offset:6144
	ds_read_b128 v[100:103], v80 offset:6656
	s_waitcnt lgkmcnt(12)
	v_mfma_f32_32x32x16_bf16 v[20:35], v[140:143], v[68:71], v[20:35]
	v_exp_f32_e32 v56, v56
	v_exp_f32_e32 v57, v57
	v_exp_f32_e32 v58, v58
	v_exp_f32_e32 v59, v59
	s_waitcnt lgkmcnt(10)
	v_mfma_f32_32x32x16_bf16 v[4:19], v[132:135], v[72:75], v[4:19]
	v_exp_f32_e32 v60, v60
	v_exp_f32_e32 v61, v61
	v_exp_f32_e32 v62, v62
	v_exp_f32_e32 v63, v63
	s_waitcnt lgkmcnt(8)
	v_mfma_f32_32x32x16_bf16 v[20:35], v[132:135], v[76:79], v[20:35]
	v_exp_f32_e32 v64, v64
	v_exp_f32_e32 v65, v65
	v_exp_f32_e32 v66, v66
	v_exp_f32_e32 v67, v67
	s_waitcnt vmcnt(0) lgkmcnt(0)
	s_barrier
	v_add_u32_e32 v168, s25, v190
	ds_read_b64_tr_b16 v[164:165], v168 offset:24576
	ds_read_b64_tr_b16 v[166:167], v168 offset:25088
	v_add_f32_e32 v68, v84, v85
	v_add_f32_e32 v68, v86, v68
	v_add_f32_e32 v68, v87, v68
	v_add_f32_e32 v68, v88, v68
	v_add_f32_e32 v132, v89, v68
	v_cvt_pk_bf16_f32 v152, v84, v85
	v_cvt_pk_bf16_f32 v153, v86, v87
	s_waitcnt lgkmcnt(9)
	v_mfma_f32_32x32x16_bf16 v[68:83], v[116:119], v[160:163], v[36:51]
	ds_read_b64_tr_b16 v[84:85], v168 offset:28672
	ds_read_b64_tr_b16 v[86:87], v168 offset:29184
	v_add_f32_e32 v116, v90, v132
	v_add_f32_e32 v116, v91, v116
	v_add_f32_e32 v116, v92, v116
	v_add_f32_e32 v116, v93, v116
	v_cvt_pk_bf16_f32 v154, v88, v89
	v_cvt_pk_bf16_f32 v155, v90, v91
	s_waitcnt lgkmcnt(10)
	v_mfma_f32_32x32x16_bf16 v[36:51], v[120:123], v[160:163], v[36:51]
	ds_read_b64_tr_b16 v[88:89], v168 offset:25600
	ds_read_b64_tr_b16 v[90:91], v168 offset:26112
	s_waitcnt lgkmcnt(11)
	v_mfma_f32_32x32x16_bf16 v[68:83], v[104:107], v[156:159], v[68:83]
	v_add_f32_e32 v104, v94, v116
	v_add_f32_e32 v104, v95, v104
	v_add_f32_e32 v104, v96, v104
	v_add_f32_e32 v104, v97, v104
	v_cvt_pk_bf16_f32 v148, v92, v93
	v_cvt_pk_bf16_f32 v149, v94, v95
	ds_read_b64_tr_b16 v[92:93], v168 offset:29696
	ds_read_b64_tr_b16 v[94:95], v168 offset:30208
	v_add_f32_e32 v104, v98, v104
	v_add_f32_e32 v104, v99, v104
	v_add_f32_e32 v104, v52, v104
	v_add_f32_e32 v104, v53, v104
	v_cvt_pk_bf16_f32 v150, v96, v97
	v_cvt_pk_bf16_f32 v151, v98, v99
	s_waitcnt lgkmcnt(12)
	v_mfma_f32_32x32x16_bf16 v[36:51], v[124:127], v[156:159], v[36:51]
	ds_read_b64_tr_b16 v[96:97], v168 offset:26624
	ds_read_b64_tr_b16 v[98:99], v168 offset:27136
	v_add_f32_e32 v104, v54, v104
	v_add_f32_e32 v104, v55, v104
	v_add_f32_e32 v104, v56, v104
	v_add_f32_e32 v104, v57, v104
	v_cvt_pk_bf16_f32 v140, v52, v53
	v_cvt_pk_bf16_f32 v141, v54, v55
	s_waitcnt lgkmcnt(13)
	v_mfma_f32_32x32x16_bf16 v[68:83], v[108:111], v[144:147], v[68:83]
	ds_read_b64_tr_b16 v[52:53], v168 offset:30720
	ds_read_b64_tr_b16 v[54:55], v168 offset:31232
	v_add_f32_e32 v104, v58, v104
	v_add_f32_e32 v104, v59, v104
	v_add_f32_e32 v104, v60, v104
	v_add_f32_e32 v104, v61, v104
	v_cvt_pk_bf16_f32 v142, v56, v57
	v_cvt_pk_bf16_f32 v143, v58, v59
	s_waitcnt lgkmcnt(14)
	v_mfma_f32_32x32x16_bf16 v[36:51], v[128:131], v[144:147], v[36:51]
	ds_read_b64_tr_b16 v[56:57], v168 offset:27648
	ds_read_b64_tr_b16 v[58:59], v168 offset:28160
	v_add_f32_e32 v104, v62, v104
	v_add_f32_e32 v104, v63, v104
	v_add_f32_e32 v104, v64, v104
	v_add_f32_e32 v104, v65, v104
	v_cvt_pk_bf16_f32 v132, v60, v61
	v_cvt_pk_bf16_f32 v133, v62, v63
	s_waitcnt lgkmcnt(14)
	v_mfma_f32_32x32x16_bf16 v[68:83], v[112:115], v[136:139], v[68:83]
	ds_read_b64_tr_b16 v[60:61], v168 offset:31744
	ds_read_b64_tr_b16 v[62:63], v168 offset:32256
	v_mfma_f32_32x32x16_bf16 v[36:51], v[100:103], v[136:139], v[36:51]
	v_add_f32_e32 v100, v66, v104
	v_add_f32_e32 v100, v67, v100
	v_add_f32_e32 v100, 0, v100
	v_cvt_pk_bf16_f32 v134, v64, v65
	v_cvt_pk_bf16_f32 v135, v66, v67
	s_waitcnt lgkmcnt(14)
	v_mfma_f32_32x32x16_bf16 v[4:19], v[152:155], v[164:167], v[4:19]
	s_nop 1
	v_exp_f32_e32 v68, v68
	v_exp_f32_e32 v69, v69
	v_exp_f32_e32 v70, v70
	v_exp_f32_e32 v71, v71
	s_waitcnt lgkmcnt(12)
	v_mfma_f32_32x32x16_bf16 v[20:35], v[152:155], v[84:87], v[20:35]
	v_exp_f32_e32 v72, v72
	v_exp_f32_e32 v73, v73
	v_exp_f32_e32 v74, v74
	v_exp_f32_e32 v75, v75
	s_waitcnt lgkmcnt(10)
	v_mfma_f32_32x32x16_bf16 v[4:19], v[148:151], v[88:91], v[4:19]
	v_exp_f32_e32 v76, v76
	v_exp_f32_e32 v77, v77
	v_exp_f32_e32 v78, v78
	v_exp_f32_e32 v79, v79
	s_waitcnt lgkmcnt(8)
	v_mfma_f32_32x32x16_bf16 v[20:35], v[148:151], v[92:95], v[20:35]
	v_exp_f32_e32 v80, v80
	v_exp_f32_e32 v81, v81
	v_exp_f32_e32 v82, v82
	v_exp_f32_e32 v83, v83
	s_waitcnt lgkmcnt(6)
	v_mfma_f32_32x32x16_bf16 v[4:19], v[140:143], v[96:99], v[4:19]
	v_exp_f32_e32 v36, v36
	v_exp_f32_e32 v37, v37
	v_exp_f32_e32 v38, v38
	v_exp_f32_e32 v39, v39
	s_waitcnt lgkmcnt(4)
	v_mfma_f32_32x32x16_bf16 v[20:35], v[140:143], v[52:55], v[20:35]
	v_exp_f32_e32 v40, v40
	v_exp_f32_e32 v41, v41
	v_exp_f32_e32 v42, v42
	v_exp_f32_e32 v43, v43
	s_waitcnt lgkmcnt(2)
	v_mfma_f32_32x32x16_bf16 v[4:19], v[132:135], v[56:59], v[4:19]
	v_exp_f32_e32 v44, v44
	v_exp_f32_e32 v45, v45
	v_exp_f32_e32 v46, v46
	v_exp_f32_e32 v47, v47
	s_waitcnt lgkmcnt(0)
	v_mfma_f32_32x32x16_bf16 v[20:35], v[132:135], v[60:63], v[20:35]
	v_exp_f32_e32 v48, v48
	v_exp_f32_e32 v49, v49
	v_exp_f32_e32 v50, v50
	v_exp_f32_e32 v51, v51
	v_add_f32_e32 v52, v68, v69
	v_add_f32_e32 v52, v70, v52
	v_add_f32_e32 v52, v71, v52
	v_add_f32_e32 v52, v72, v52
	v_add_f32_e32 v52, v73, v52
	v_add_f32_e32 v52, v74, v52
	v_add_f32_e32 v52, v75, v52
	v_add_f32_e32 v52, v76, v52
	v_add_f32_e32 v52, v77, v52
	v_add_f32_e32 v52, v78, v52
	v_add_f32_e32 v52, v79, v52
	v_add_f32_e32 v52, v80, v52
	v_add_f32_e32 v52, v81, v52
	v_add_f32_e32 v52, v82, v52
	v_add_f32_e32 v52, v83, v52
	v_add_f32_e32 v52, v36, v52
	v_add_f32_e32 v52, v37, v52
	v_add_f32_e32 v52, v38, v52
	v_add_f32_e32 v52, v39, v52
	v_add_f32_e32 v52, v40, v52
	v_add_f32_e32 v52, v41, v52
	v_add_f32_e32 v52, v42, v52
	v_add_f32_e32 v52, v43, v52
	v_add_f32_e32 v52, v44, v52
	v_add_f32_e32 v52, v45, v52
	v_add_f32_e32 v52, v46, v52
	v_add_f32_e32 v52, v47, v52
	v_add_f32_e32 v52, v48, v52
	v_add_f32_e32 v52, v49, v52
	v_add_f32_e32 v52, v50, v52
	v_add_f32_e32 v52, v51, v52
	v_add_f32_e32 v1, v1, v100
	v_add_f32_e32 v1, v1, v52
	v_cvt_pk_bf16_f32 v52, v68, v69
	v_cvt_pk_bf16_f32 v53, v70, v71
	v_cvt_pk_bf16_f32 v54, v72, v73
	v_cvt_pk_bf16_f32 v55, v74, v75
	v_cvt_pk_bf16_f32 v56, v76, v77
	v_cvt_pk_bf16_f32 v57, v78, v79
	v_cvt_pk_bf16_f32 v58, v80, v81
	v_cvt_pk_bf16_f32 v59, v82, v83
	v_cvt_pk_bf16_f32 v36, v36, v37
	v_cvt_pk_bf16_f32 v37, v38, v39
	v_cvt_pk_bf16_f32 v38, v40, v41
	v_cvt_pk_bf16_f32 v39, v42, v43
	v_cvt_pk_bf16_f32 v40, v44, v45
	v_cvt_pk_bf16_f32 v41, v46, v47
	v_cvt_pk_bf16_f32 v42, v48, v49
	v_cvt_pk_bf16_f32 v43, v50, v51
	v_add3_u32 v0, v0, v3, s24
	ds_read_b64_tr_b16 v[44:45],v0 offset:0
	ds_read_b64_tr_b16 v[46:47],v0 offset:512
	ds_read_b64_tr_b16 v[48:49],v0 offset:1024
	ds_read_b64_tr_b16 v[50:51],v0 offset:1536
	ds_read_b64_tr_b16 v[60:61],v0 offset:2048
	ds_read_b64_tr_b16 v[62:63],v0 offset:2560
	ds_read_b64_tr_b16 v[64:65],v0 offset:3072
	ds_read_b64_tr_b16 v[66:67],v0 offset:3584
	s_waitcnt lgkmcnt(0)
	s_nop 0
	v_mfma_f32_32x32x16_bf16 v[4:19], v[52:55], v[44:47], v[4:19]
	ds_read_b64_tr_b16 v[44:45],v0 offset:4096
	ds_read_b64_tr_b16 v[46:47],v0 offset:4608
	v_mfma_f32_32x32x16_bf16 v[4:19], v[56:59], v[48:51], v[4:19]
	ds_read_b64_tr_b16 v[48:49],v0 offset:5120
	ds_read_b64_tr_b16 v[50:51],v0 offset:5632
	v_mfma_f32_32x32x16_bf16 v[4:19], v[36:39], v[60:63], v[4:19]
	ds_read_b64_tr_b16 v[60:61],v0 offset:6144
	ds_read_b64_tr_b16 v[62:63],v0 offset:6656
	v_mfma_f32_32x32x16_bf16 v[4:19], v[40:43], v[64:67], v[4:19]
	ds_read_b64_tr_b16 v[64:65],v0 offset:7168
	ds_read_b64_tr_b16 v[66:67],v0 offset:7680
	s_waitcnt lgkmcnt(0)
	v_mfma_f32_32x32x16_bf16 v[20:35], v[52:55], v[44:47], v[20:35]
	v_mfma_f32_32x32x16_bf16 v[20:35], v[56:59], v[48:51], v[20:35]
	v_mfma_f32_32x32x16_bf16 v[20:35], v[36:39], v[60:63], v[20:35]
	v_mfma_f32_32x32x16_bf16 v[20:35], v[40:43], v[64:67], v[20:35]
	s_setprio 0
	v_mov_b32_e32 v0, v1
	s_nop 1
	v_permlane32_swap_b32_e32 v1, v0
	v_cmp_gt_u32_e32 vcc, 32, v186
	s_and_saveexec_b64 s[24:25], vcc
	s_cbranch_execz .LBB0_727
	v_lshl_add_u32 v3, v188, 2, s28
	v_add_f32_e32 v0, v1, v0
	ds_write_b32 v3, v0 offset:49280
	s_branch .LBB0_727
